# prompt chunk loop: k/q cooperative loads remapped to full 128-byte-line requests
# speedup vs baseline: 1.0027x; 1.0011x over previous
.LBB0_2534:
	s_or_b64 exec, exec, s[6:7]
	s_and_b32 s35, s2, 63
	s_add_u32 s6, s64, s4
	s_addc_u32 s7, s65, 0
	v_mov_b32_e32 v2, 0
	v_mov_b32_e32 v97, v2
	s_add_u32 s5, s14, s4
	v_lshl_add_u64 v[98:99], s[6:7], 0, v[96:97]
	s_addc_u32 s12, s15, 0
	s_lshl_b64 s[6:7], s[8:9], 1
	s_add_u32 s6, s5, s6
	s_addc_u32 s7, s12, s7
	s_add_u32 s12, s6, s10
	s_addc_u32 s13, s7, 0
	v_lshlrev_b32_e32 v5, 4, v14
	v_lshlrev_b32_e32 v14, 1, v95
	v_mov_b32_e32 v15, v2
	s_add_u32 s4, s20, s4
	v_lshl_add_u64 v[100:101], s[12:13], 0, v[14:15]
	s_addc_u32 s5, s21, 0
	s_add_i32 s18, 0, 0x11400
	s_lshl_b32 s12, s38, 5
	s_add_u32 s12, s28, s12
	s_addc_u32 s13, s29, 0
	v_mov_b32_e32 v11, v2
	s_add_u32 s12, s12, 0xf191400
	v_or_b32_e32 v16, s16, v1
	v_or_b32_e32 v17, s16, v95
	v_lshl_add_u64 v[102:103], s[4:5], 0, v[10:11]
	v_lshlrev_b32_e32 v10, 4, v13
	s_addc_u32 s13, s13, 0
	v_lshl_add_u64 v[104:105], s[6:7], 0, v[14:15]
	s_add_i32 s6, 0, 0x15c00
	s_movk_i32 s7, 0x90
	v_add_u32_e32 v18, s18, v10
	v_add_u32_e32 v14, s6, v10
	v_mul_lo_u32 v10, v17, s7
	v_lshlrev_b32_e32 v11, 1, v117
	v_mul_lo_u32 v125, v16, s7
	s_movk_i32 s7, 0x48
	v_add3_u32 v123, 0, v10, v11
	v_mul_lo_u32 v10, v17, s7
	v_add_lshl_u32 v10, v10, v117, 1
	v_add_u32_e32 v11, 0x90, v10
	v_add_u32_e32 v128, s18, v11
	v_add_u32_e32 v129, s6, v11
	v_add_u32_e32 v11, 0x120, v10
	v_add_u32_e32 v130, s18, v11
	v_add_u32_e32 v131, s6, v11
	v_add_u32_e32 v11, 0x1b0, v10
	v_add_u32_e32 v132, s18, v11
	v_add_u32_e32 v133, s6, v11
	v_add_u32_e32 v11, 0x900, v10
	v_add_u32_e32 v134, s18, v11
	v_add_u32_e32 v135, s6, v11
	v_add_u32_e32 v11, 0x990, v10
	v_add_u32_e32 v126, s18, v10
	v_add_u32_e32 v127, s6, v10
	v_add_u32_e32 v136, s18, v11
	v_add_u32_e32 v137, s6, v11
	v_add_u32_e32 v11, 0xa20, v10
	v_add_u32_e32 v10, 0xab0, v10
	v_add_u32_e32 v139, s6, v11
	v_add_u32_e32 v141, s6, v10
	s_add_i32 s6, s16, s8
	s_ashr_i32 s16, s6, 4
	s_add_i32 s6, s6, 16
	s_add_i32 s44, s44, s38
	v_add_u32_e32 v138, s18, v11
	v_add_u32_e32 v140, s18, v10
	s_ashr_i32 s18, s6, 4
	s_lshl_b32 s6, s44, 14
	s_mul_i32 s40, s40, 0x8400
	s_add_i32 s38, s6, 0x20000
	s_or_b32 s6, s41, s40
	v_add_lshl_u32 v10, s6, v116, 2
	v_mov_b32_e32 v11, v2
	s_movk_i32 s17, 0x110
	v_lshl_add_u64 v[10:11], s[28:29], 0, v[10:11]
	s_mov_b64 s[6:7], 0xf006400
	s_lshr_b32 s45, s44, 3
	v_or_b32_e32 v119, 32, v94
	s_mov_b32 s11, 0
	v_lshl_add_u32 v122, v94, 1, 0
	v_mul_lo_u32 v15, v16, s17
	v_mul_u32_u24_e32 v16, 0x90, v1
	v_lshl_add_u64 v[106:107], v[10:11], 0, s[6:7]
	s_lshl_b32 s6, s45, 6
	v_add_u32_e32 v148, v12, v4
	v_mbcnt_lo_u32_b32 v4, -1, 0
	v_mul_u32_u24_e32 v120, 0x110, v118
	v_mul_u32_u24_e32 v121, 0x110, v117
	v_cmp_eq_u32_e64 s[4:5], 0, v13
	v_add_u32_e32 v124, 0x900, v123
	s_ashr_i32 s17, s16, 31
	s_ashr_i32 s19, s18, 31
	v_mul_u32_u24_e32 v142, 0x880, v13
	v_mul_u32_u24_e32 v143, 0x110, v119
	s_mov_b32 s39, s11
	s_sub_i32 s46, s6, 64
	s_sub_i32 s47, 0, s45
	v_lshlrev_b32_e32 v144, 1, v5
	v_add_u32_e32 v145, v122, v15
	v_add_u32_e32 v146, v18, v125
	s_mov_b32 s48, 0x5040100
	v_add_u32_e32 v147, v14, v16
	s_mov_b64 s[40:41], 0x1000
	v_mbcnt_hi_u32_b32 v149, -1, v4
	s_mov_b32 s49, s44
	s_mov_b32 s50, s11
	s_mov_b32 s51, s11
	v_mov_b32_e32 v22, 0
	v_mov_b32_e32 v23, v2
	v_mov_b32_e32 v24, v2
	v_mov_b32_e32 v25, v2
	v_mov_b32_e32 v18, 0
	v_mov_b32_e32 v19, v2
	v_mov_b32_e32 v20, v2
	v_mov_b32_e32 v21, v2
	v_mov_b32_e32 v14, 0
	v_mov_b32_e32 v15, v2
	v_mov_b32_e32 v16, v2
	v_mov_b32_e32 v17, v2
	v_mov_b32_e32 v10, 0
	v_mov_b32_e32 v11, v2
	v_mov_b32_e32 v12, v2
	v_mov_b32_e32 v13, v2
	v_and_b32_e32 v222, 7, v116
	v_lshlrev_b32_e32 v223, 4, v222
	v_lshrrev_b32_e32 v225, 4, v116
	v_and_b32_e32 v232, 15, v116
	v_lshlrev_b32_e32 v232, 4, v232
	v_mul_u32_u24_e32 v204, 0x110, v225
	v_add_u32_e32 v204, v204, v232
	v_lshlrev_b32_e32 v225, 11, v225
	v_add_u32_e32 v225, v225, v232
	v_add_u32_e32 v205, v121, v96
	v_mul_u32_u24_e32 v216, 0x90, v118
	v_add_u32_e32 v216, v216, v223
	v_add_u32_e32 v217, 0x13800, v216
	v_add_u32_e32 v218, 0x18000, v216
	v_mul_u32_u24_e32 v219, 0x90, v117
	v_add_u32_e32 v221, v219, v94
	v_add_u32_e32 v221, s10, v221
	v_add_u32_e32 v221, 0x18000, v221
	v_add_u32_e32 v219, v219, v96
	v_add_u32_e32 v220, 0x13800, v219
	s_and_b32 s66, s2, 7
	s_bfe_u32 s67, s2, 0x30003
	s_lshl_b32 s68, s66, 8
	s_and_b32 s69, s2, 64
	s_lshl_b32 s69, s69, 1
	v_lshlrev_b32_e32 v224, 11, v118
	v_add_u32_e32 v224, s68, v224
	v_mov_b32_e32 v227, 0
	v_mov_b32_e32 v229, 0
	v_add_u32_e32 v226, s68, v225
	v_add_u32_e32 v228, v224, v223
	v_add_u32_e32 v228, s69, v228
	s_lshl_b32 s70, s67, 4
	s_add_i32 s70, s70, 0x4400
	s_lshl_b32 s70, s70, 11
	s_add_u32 s36, s20, s70
	s_addc_u32 s37, s21, 0
	v_lshl_add_u64 v[206:207], s[36:37], 0, v[226:227]
	s_add_u32 s36, s64, s70
	s_addc_u32 s37, s65, 0
	v_lshl_add_u64 v[208:209], s[36:37], 0, v[226:227]
	s_add_u32 s36, s14, s70
	s_addc_u32 s37, s15, 0
	v_lshl_add_u64 v[210:211], s[36:37], 0, v[228:229]
	s_mul_i32 s70, s67, 0x108
	s_add_i32 s70, s70, s66
	s_lshl_b32 s71, s70, 14
	s_add_u32 s36, s62, s71
	s_addc_u32 s37, s63, 0
	v_lshlrev_b32_e32 v230, 4, v116
	v_mov_b32_e32 v231, 0
	v_lshl_add_u64 v[212:213], s[36:37], 0, v[230:231]
	v_add_u32_e32 v230, 0x2000, v230
	v_lshl_add_u64 v[214:215], s[36:37], 0, v[230:231]
	v_mov_b32_e32 v38, 0
	v_mov_b32_e32 v39, 0
	v_mov_b64_e32 v[40:41], v[38:39]
	v_mov_b64_e32 v[42:43], v[38:39]
	v_mov_b64_e32 v[44:45], v[38:39]
	v_mov_b64_e32 v[62:63], v[38:39]
	v_mov_b64_e32 v[64:65], v[38:39]
	v_mov_b64_e32 v[66:67], v[38:39]
	v_mov_b64_e32 v[68:69], v[38:39]
	v_mov_b64_e32 v[78:79], v[38:39]
	v_mov_b64_e32 v[80:81], v[38:39]
	v_cmp_gt_u32_e32 vcc, 16, v118
	s_and_saveexec_b64 s[70:71], vcc
	global_load_dwordx4 v[78:81], v[210:211], off nt
	s_or_b64 exec, exec, s[70:71]
	s_movk_i32 s70, 0x100
	v_cmp_gt_u32_e32 vcc, s70, v116
	s_and_saveexec_b64 s[70:71], vcc
	global_load_dwordx4 v[42:45], v[206:207], off
	global_load_dwordx4 v[62:65], v[208:209], off
	s_or_b64 exec, exec, s[70:71]
	global_load_dwordx4 v[70:73], v[212:213], off
	global_load_dwordx4 v[74:77], v[214:215], off
	s_lshl_b32 s70, s67, 22
	s_add_u32 s36, s20, s70
	s_addc_u32 s37, s21, 0
	v_lshl_add_u64 v[206:207], s[36:37], 0, v[226:227]
	s_add_u32 s36, s64, s70
	s_addc_u32 s37, s65, 0
	v_lshl_add_u64 v[208:209], s[36:37], 0, v[226:227]
	s_add_u32 s36, s14, s70
	s_addc_u32 s37, s15, 0
	v_lshl_add_u64 v[210:211], s[36:37], 0, v[228:229]
	s_mov_b32 s36, 0x10000
	s_mov_b32 s37, 0
	v_lshl_add_u64 v[232:233], v[206:207], 0, s[36:37]
	v_lshl_add_u64 v[234:235], v[208:209], 0, s[36:37]
	s_mov_b32 s36, 0x20000
	v_lshl_add_u64 v[212:213], v[212:213], 0, s[36:37]
	v_lshl_add_u64 v[214:215], v[214:215], 0, s[36:37]
	s_waitcnt vmcnt(0)
	s_branch .LBB0_2537

.LBB0_2540:
	s_and_b32 s6, s51, 1
	s_mul_i32 s7, s6, 0x12000
	s_mulk_i32 s6, 0x4800
	s_add_i32 s55, s6, 0
	s_add_i32 s52, s7, 0
	s_add_i32 s55, s55, 0x1a400
	v_add_u32_e32 v4, s52, v204
	s_waitcnt vmcnt(4)
	ds_write_b128 v4, v[42:45] offset:34816
	ds_write_b128 v4, v[38:41] offset:43520
	ds_write_b128 v204, v[62:65] offset:17408
	ds_write_b128 v204, v[66:69] offset:26112
	ds_write_b128 v216, v[70:73] offset:61440
	ds_write_b128 v217, v[74:77]
	ds_write_b128 v218, v[78:81]
	s_and_saveexec_b64 s[6:7], s[0:1]
	v_lshl_add_u32 v4, v116, 2, s55
	ds_write_b32 v4, v3
	s_or_b64 exec, exec, s[6:7]
	s_cmpk_eq_i32 s50, 0x100
	s_waitcnt lgkmcnt(0)
	s_barrier
	s_cbranch_scc1 .LBB0_2572
	global_load_dwordx4 v[42:45], v[206:207], off
	global_load_dwordx4 v[38:41], v[232:233], off
	global_load_dwordx4 v[62:65], v[208:209], off
	global_load_dwordx4 v[66:69], v[234:235], off
	global_load_dwordx4 v[78:81], v[210:211], off nt
	global_load_dwordx4 v[70:73], v[212:213], off
	global_load_dwordx4 v[74:77], v[214:215], off
	s_and_saveexec_b64 s[6:7], s[0:1]
	global_load_dword v3, v[106:107], off
	s_or_b64 exec, exec, s[6:7]
	v_lshl_add_u64 v[232:233], v[232:233], 0, s[36:37]
	v_lshl_add_u64 v[234:235], v[234:235], 0, s[36:37]
	v_lshl_add_u64 v[206:207], v[206:207], 0, s[36:37]
	v_lshl_add_u64 v[208:209], v[208:209], 0, s[36:37]
	v_lshl_add_u64 v[210:211], v[210:211], 0, s[36:37]
	v_lshl_add_u64 v[212:213], v[212:213], 0, s[36:37]
	v_lshl_add_u64 v[214:215], v[214:215], 0, s[36:37]
